# hoist the 8 serialized row-rstd loads in the FFN-in (SwiGLU) GEMM epilogue; counted vmcnt waits
# speedup vs baseline: 1.0915x; 1.0915x over previous
; __device__ __forceinline__ float row_rstd(const float* ssp, int row, int fq) {
;     const f32x4 t = *((const f32x4*)(ssp + (size_t)row * 16) + fq); float s = (t[0] + t[1]) + (t[2] + t[3]); s += __shfl_xor(s, 16); s += __shfl_xor(s, 32); return rsqrtf(s * (1.0f / DM) + EPS); }
;     __device__ __forceinline__ void operator()(const f32x4 (&acc)[2][2][4][2], const Unit& u, int wr, int wc, int fr, int fq) const {
;         const int row0 = u.pm * BM + wr * 64 + fr, col0 = u.pn * 128 + 32 * wc + 8 * fq, lrow0 = row0 & (SEQ - 1);
;         bf16_t* const H = (bf16_t*)(ws + WS_SLAB + (size_t)(u.pm >> 4) * SLAB + SL_H);
;         float rx[2][4];
; #pragma unroll
;         for (int ai = 0; ai < 2; ++ai)
; #pragma unroll
;             for (int m = 0; m < 4; ++m) rx[ai][m] = row_rstd(ssp, row0 + ai * HALF + m * 16, fq);
; #pragma unroll
;         for (int ai = 0; ai < 2; ++ai)
; #pragma unroll
;             for (int m = 0; m < 4; ++m) { f32x4 o[2];
; #pragma unroll
;                 for (int n = 0; n < 2; ++n) { const f32x4 a = acc[ai][0][m][n] * rx[ai][m], b = acc[ai][1][m][n] * rx[ai][m];
.LBB0_580:
	v_and_b32_e32 v129, 64, v229
	v_xor_b32_e32 v128, 16, v229
	v_add_u32_e32 v129, 64, v129
	v_cmp_lt_i32_e32 vcc, v128, v129
	v_lshl_add_u32 v130, s42, 8, v147
	v_ashrrev_i32_e32 v131, 31, v130
	v_cndmask_b32_e32 v128, v229, v128, vcc
	v_lshlrev_b32_e32 v162, 2, v128
	v_xor_b32_e32 v128, 32, v229
	v_cmp_lt_i32_e32 vcc, v128, v129
	s_mov_b32 s4, 0x358637bd
	s_ashr_i32 s29, s42, 4
	v_cndmask_b32_e32 v128, v229, v128, vcc
	v_lshlrev_b32_e32 v157, 2, v128
	v_lshlrev_b64 v[128:129], 6, v[130:131]
	v_lshl_add_u64 v[128:129], v[140:141], 0, v[128:129]
	global_load_dwordx4 v[170:173], v[128:129], off
	global_load_dwordx4 v[174:177], v[128:129], off offset:1024
	global_load_dwordx4 v[178:181], v[128:129], off offset:2048
	global_load_dwordx4 v[182:185], v[128:129], off offset:3072
	v_add_co_u32_e32 v206, vcc, s82, v128
	s_nop 0
	v_addc_co_u32_e32 v207, vcc, 0, v129, vcc
	global_load_dwordx4 v[186:189], v[206:207], off
	global_load_dwordx4 v[194:197], v[206:207], off offset:1024
	global_load_dwordx4 v[198:201], v[206:207], off offset:2048
	global_load_dwordx4 v[202:205], v[206:207], off offset:3072
	v_and_b32_e32 v155, 0xfcf, v130
	s_mul_hi_i32 s27, s29, 0x1c00000
	s_mul_i32 s29, s29, 0x1c00000
	s_add_u32 s10, s56, s29
	s_addc_u32 s11, s57, s27
	s_waitcnt vmcnt(7)
	v_mov_b32_e32 v164, v171
	v_mov_b32_e32 v165, v172
	v_mov_b32_e32 v171, v173
	v_pk_add_f32 v[164:165], v[164:165], v[170:171]
	s_waitcnt vmcnt(6)
	v_mov_b32_e32 v166, v175
	v_mov_b32_e32 v167, v176
	v_mov_b32_e32 v175, v177
	v_pk_add_f32 v[158:159], v[166:167], v[174:175]
	v_mov_b32_e32 v161, v164
	v_mov_b32_e32 v160, v158
	v_mov_b32_e32 v164, v159
	v_pk_add_f32 v[158:159], v[160:161], v[164:165]
	ds_bpermute_b32 v161, v162, v159
	ds_bpermute_b32 v160, v162, v158
	s_waitcnt lgkmcnt(0)
	v_pk_add_f32 v[158:159], v[158:159], v[160:161]
	ds_bpermute_b32 v161, v157, v159
	ds_bpermute_b32 v160, v157, v158
	s_waitcnt lgkmcnt(0)
	v_pk_add_f32 v[160:161], v[158:159], v[160:161]
	v_mov_b64_e32 v[158:159], s[4:5]
	v_pk_fma_f32 v[160:161], v[160:161], s[38:39], v[158:159] op_sel_hi:[1,0,0]
	s_nop 0
	v_mul_f32_e32 v131, 0x4b800000, v161
	v_cmp_gt_f32_e64 s[42:43], s99, v161
	v_cmp_gt_f32_e32 vcc, s99, v160
	s_nop 0
	v_cndmask_b32_e64 v131, v161, v131, s[42:43]
	v_rsq_f32_e32 v131, v131
	s_nop 0
	v_mul_f32_e32 v146, 0x45800000, v131
	v_cndmask_b32_e64 v156, v131, v146, s[42:43]
	v_mul_f32_e32 v131, 0x4b800000, v160
	v_cndmask_b32_e32 v131, v160, v131, vcc
	v_rsq_f32_e32 v131, v131
	v_pk_mul_f32 v[124:125], v[124:125], v[156:157] op_sel_hi:[1,0]
	v_pk_mul_f32 v[120:121], v[120:121], v[156:157] op_sel_hi:[1,0]
	v_mul_f32_e32 v146, 0x45800000, v131
	v_cndmask_b32_e32 v154, v131, v146, vcc
	v_pk_mul_f32 v[122:123], v[122:123], v[156:157] op_sel_hi:[1,0]
	v_pk_mul_f32 v[116:117], v[116:117], v[156:157] op_sel_hi:[1,0]
	v_pk_mul_f32 v[112:113], v[112:113], v[156:157] op_sel_hi:[1,0]
	v_pk_mul_f32 v[114:115], v[114:115], v[156:157] op_sel_hi:[1,0]
	v_pk_mul_f32 v[108:109], v[108:109], v[154:155] op_sel_hi:[1,0]
	v_pk_mul_f32 v[104:105], v[104:105], v[154:155] op_sel_hi:[1,0]
	v_pk_mul_f32 v[106:107], v[106:107], v[154:155] op_sel_hi:[1,0]
	v_pk_mul_f32 v[100:101], v[100:101], v[154:155] op_sel_hi:[1,0]
	v_pk_mul_f32 v[96:97], v[96:97], v[154:155] op_sel_hi:[1,0]
	v_pk_mul_f32 v[98:99], v[98:99], v[154:155] op_sel_hi:[1,0]
	s_waitcnt vmcnt(5)
	v_mov_b32_e32 v160, v179
	v_mov_b32_e32 v161, v180
	v_mov_b32_e32 v179, v181
	v_pk_add_f32 v[160:161], v[160:161], v[178:179]
	s_waitcnt vmcnt(4)
	v_mov_b32_e32 v130, v183
	v_mov_b32_e32 v131, v184
	v_mov_b32_e32 v183, v185
	v_pk_add_f32 v[130:131], v[130:131], v[182:183]
	v_mov_b32_e32 v165, v160
	v_mov_b32_e32 v164, v130
	v_mov_b32_e32 v160, v131
	v_pk_add_f32 v[130:131], v[164:165], v[160:161]
	ds_bpermute_b32 v161, v162, v131
	ds_bpermute_b32 v160, v162, v130
	s_waitcnt lgkmcnt(0)
	v_pk_add_f32 v[130:131], v[130:131], v[160:161]
	ds_bpermute_b32 v161, v157, v131
	ds_bpermute_b32 v160, v157, v130
	s_waitcnt lgkmcnt(0)
	v_pk_add_f32 v[130:131], v[130:131], v[160:161]
	s_nop 0
	v_pk_fma_f32 v[130:131], v[130:131], s[38:39], v[158:159] op_sel_hi:[1,0,0]
	s_nop 0
	v_mul_f32_e32 v146, 0x4b800000, v131
	v_cmp_gt_f32_e64 s[42:43], s99, v131
	v_cmp_gt_f32_e32 vcc, s99, v130
	s_nop 0
	v_cndmask_b32_e64 v131, v131, v146, s[42:43]
	v_rsq_f32_e32 v131, v131
	s_nop 0
	v_mul_f32_e32 v146, 0x45800000, v131
	v_cndmask_b32_e64 v152, v131, v146, s[42:43]
	v_mul_f32_e32 v131, 0x4b800000, v130
	v_cndmask_b32_e32 v130, v130, v131, vcc
	v_rsq_f32_e32 v130, v130
	v_pk_mul_f32 v[92:93], v[92:93], v[152:153] op_sel_hi:[1,0]
	v_pk_mul_f32 v[88:89], v[88:89], v[152:153] op_sel_hi:[1,0]
	v_pk_mul_f32 v[90:91], v[90:91], v[152:153] op_sel_hi:[1,0]
	v_mul_f32_e32 v131, 0x45800000, v130
	v_cndmask_b32_e32 v150, v130, v131, vcc
	v_pk_mul_f32 v[84:85], v[84:85], v[152:153] op_sel_hi:[1,0]
	v_pk_mul_f32 v[80:81], v[80:81], v[152:153] op_sel_hi:[1,0]
	v_pk_mul_f32 v[82:83], v[82:83], v[152:153] op_sel_hi:[1,0]
	v_pk_mul_f32 v[76:77], v[76:77], v[150:151] op_sel_hi:[1,0]
	v_pk_mul_f32 v[72:73], v[72:73], v[150:151] op_sel_hi:[1,0]
	v_pk_mul_f32 v[74:75], v[74:75], v[150:151] op_sel_hi:[1,0]
	v_pk_mul_f32 v[68:69], v[68:69], v[150:151] op_sel_hi:[1,0]
	v_pk_mul_f32 v[64:65], v[64:65], v[150:151] op_sel_hi:[1,0]
	v_pk_mul_f32 v[66:67], v[66:67], v[150:151] op_sel_hi:[1,0]
	s_waitcnt vmcnt(3)
	v_mov_b32_e32 v130, v187
	v_mov_b32_e32 v131, v188
	v_mov_b32_e32 v187, v189
	v_pk_add_f32 v[130:131], v[130:131], v[186:187]
	s_waitcnt vmcnt(2)
; __device__ __forceinline__ u32x4 pack8(const f32x4& a, const f32x4& b) { u32x4 w; w.x = pk2(a[0], a[1]); w.y = pk2(a[2], a[3]); w.z = pk2(b[0], b[1]); w.w = pk2(b[2], b[3]); return w; }
; __device__ __forceinline__ float sigm(float x) { return __builtin_amdgcn_rcpf(1.0f + __builtin_amdgcn_exp2f(x * -1.4426950408889634f)); }
;     __device__ __forceinline__ void operator()(const f32x4 (&acc)[2][2][4][2], const Unit& u, int wr, int wc, int fr, int fq) const {
;     ...
;             for (int m = 0; m < 4; ++m) rx[ai][m] = row_rstd(ssp, row0 + ai * HALF + m * 16, fq);
; #pragma unroll
;         for (int ai = 0; ai < 2; ++ai)
; #pragma unroll
;             for (int m = 0; m < 4; ++m) { f32x4 o[2];
; #pragma unroll
;                 for (int n = 0; n < 2; ++n) { const f32x4 a = acc[ai][0][m][n] * rx[ai][m], b = acc[ai][1][m][n] * rx[ai][m];
; #pragma unroll
;                     for (int e = 0; e < 4; ++e) o[n][e] = a[e] * sigm(a[e]) * b[e]; }
;                 *(u32x4*)(H + (size_t)(lrow0 + ai * HALF + m * 16) * DFF + col0) = pack8(o[0], o[1]); asm volatile("" ::: "memory"); }
	v_mov_b32_e32 v160, v195
	v_mov_b32_e32 v161, v196
	v_mov_b32_e32 v195, v197
	v_pk_add_f32 v[160:161], v[160:161], v[194:195]
	v_mov_b32_e32 v165, v130
	v_mov_b32_e32 v164, v160
	v_mov_b32_e32 v130, v161
	v_pk_add_f32 v[130:131], v[164:165], v[130:131]
	ds_bpermute_b32 v161, v162, v131
	ds_bpermute_b32 v160, v162, v130
	s_waitcnt lgkmcnt(0)
	v_pk_add_f32 v[130:131], v[130:131], v[160:161]
	ds_bpermute_b32 v161, v157, v131
	ds_bpermute_b32 v160, v157, v130
	s_waitcnt lgkmcnt(0)
	v_pk_add_f32 v[130:131], v[130:131], v[160:161]
	s_nop 0
	v_pk_fma_f32 v[130:131], v[130:131], s[38:39], v[158:159] op_sel_hi:[1,0,0]
	s_nop 0
	v_mul_f32_e32 v146, 0x4b800000, v131
	v_cmp_gt_f32_e64 s[42:43], s99, v131
	v_cmp_gt_f32_e32 vcc, s99, v130
	s_nop 0
	v_cndmask_b32_e64 v131, v131, v146, s[42:43]
	v_rsq_f32_e32 v131, v131
	s_nop 0
	v_mul_f32_e32 v146, 0x45800000, v131
	v_cndmask_b32_e64 v148, v131, v146, s[42:43]
	v_mul_f32_e32 v131, 0x4b800000, v130
	v_cndmask_b32_e32 v130, v130, v131, vcc
	v_rsq_f32_e32 v130, v130
	v_pk_mul_f32 v[60:61], v[60:61], v[148:149] op_sel_hi:[1,0]
	v_pk_mul_f32 v[56:57], v[56:57], v[148:149] op_sel_hi:[1,0]
	v_pk_mul_f32 v[58:59], v[58:59], v[148:149] op_sel_hi:[1,0]
	v_mul_f32_e32 v131, 0x45800000, v130
	v_cndmask_b32_e32 v146, v130, v131, vcc
	v_pk_mul_f32 v[52:53], v[52:53], v[148:149] op_sel_hi:[1,0]
	v_pk_mul_f32 v[48:49], v[48:49], v[148:149] op_sel_hi:[1,0]
	v_pk_mul_f32 v[50:51], v[50:51], v[148:149] op_sel_hi:[1,0]
	v_pk_mul_f32 v[44:45], v[44:45], v[146:147] op_sel_hi:[1,0]
	v_pk_mul_f32 v[40:41], v[40:41], v[146:147] op_sel_hi:[1,0]
	v_pk_mul_f32 v[42:43], v[42:43], v[146:147] op_sel_hi:[1,0]
	v_pk_mul_f32 v[36:37], v[36:37], v[146:147] op_sel_hi:[1,0]
	v_pk_mul_f32 v[32:33], v[32:33], v[146:147] op_sel_hi:[1,0]
	v_pk_mul_f32 v[34:35], v[34:35], v[146:147] op_sel_hi:[1,0]
	s_waitcnt vmcnt(1)
	v_mov_b32_e32 v130, v199
	v_mov_b32_e32 v131, v200
	v_mov_b32_e32 v199, v201
	v_pk_add_f32 v[160:161], v[130:131], v[198:199]
	s_waitcnt vmcnt(0)
	v_mov_b32_e32 v164, v203
	v_mov_b32_e32 v165, v204
	v_mov_b32_e32 v203, v205
	v_pk_add_f32 v[128:129], v[164:165], v[202:203]
	v_mov_b32_e32 v131, v160
	v_mov_b32_e32 v130, v128
	v_mov_b32_e32 v160, v129
	v_pk_add_f32 v[128:129], v[130:131], v[160:161]
	ds_bpermute_b32 v131, v162, v129
	ds_bpermute_b32 v130, v162, v128
	s_waitcnt lgkmcnt(0)
	v_pk_add_f32 v[128:129], v[128:129], v[130:131]
	ds_bpermute_b32 v131, v157, v129
	ds_bpermute_b32 v130, v157, v128
	s_waitcnt lgkmcnt(0)
	v_pk_add_f32 v[128:129], v[128:129], v[130:131]
	s_nop 0
	v_pk_fma_f32 v[128:129], v[128:129], s[38:39], v[158:159] op_sel_hi:[1,0,0]
	v_lshl_or_b32 v158, s59, 7, v151
	v_mul_f32_e32 v130, 0x4b800000, v129
	v_cmp_gt_f32_e64 s[42:43], s99, v129
	v_cmp_gt_f32_e32 vcc, s99, v128
	v_ashrrev_i32_e32 v159, 31, v158
	v_cndmask_b32_e64 v129, v129, v130, s[42:43]
	v_rsq_f32_e32 v129, v129
	v_lshl_add_u64 v[158:159], v[158:159], 1, s[10:11]
	v_mul_f32_e32 v130, 0x45800000, v129
	v_cndmask_b32_e64 v130, v129, v130, s[42:43]
	v_mul_f32_e32 v129, 0x4b800000, v128
	v_cndmask_b32_e32 v128, v128, v129, vcc
	v_rsq_f32_e32 v128, v128
	v_pk_mul_f32 v[28:29], v[28:29], v[130:131] op_sel_hi:[1,0]
	v_pk_mul_f32 v[24:25], v[24:25], v[130:131] op_sel_hi:[1,0]
	v_pk_mul_f32 v[26:27], v[26:27], v[130:131] op_sel_hi:[1,0]
	v_mul_f32_e32 v129, 0x45800000, v128
	v_cndmask_b32_e32 v128, v128, v129, vcc
	v_mul_f32_e32 v129, 0xbfb8aa3b, v124
	v_exp_f32_e32 v129, v129
	v_pk_mul_f32 v[20:21], v[20:21], v[130:131] op_sel_hi:[1,0]
	v_pk_mul_f32 v[16:17], v[16:17], v[130:131] op_sel_hi:[1,0]
	v_pk_mul_f32 v[18:19], v[18:19], v[130:131] op_sel_hi:[1,0]
	v_add_f32_e32 v129, 1.0, v129
	v_rcp_f32_e32 v160, v129
	v_mul_f32_e32 v129, 0xbfb8aa3b, v125
	v_exp_f32_e32 v129, v129
	s_mov_b64 s[42:43], -1
	v_add_f32_e32 v129, 1.0, v129
	v_rcp_f32_e32 v161, v129
	v_pk_mul_f32 v[12:13], v[12:13], v[128:129] op_sel_hi:[1,0]
	v_pk_mul_f32 v[8:9], v[8:9], v[128:129] op_sel_hi:[1,0]
	v_pk_mul_f32 v[10:11], v[10:11], v[128:129] op_sel_hi:[1,0]
	v_pk_mul_f32 v[124:125], v[124:125], v[160:161]
	v_pk_mul_f32 v[4:5], v[4:5], v[128:129] op_sel_hi:[1,0]
	v_pk_mul_f32 v[120:121], v[120:121], v[124:125]
	v_pk_mul_f32 v[124:125], v[126:127], v[156:157] op_sel_hi:[1,0]
	v_pk_mul_f32 v[0:1], v[0:1], v[128:129] op_sel_hi:[1,0]
	v_mul_f32_e32 v126, 0xbfb8aa3b, v124
	v_mul_f32_e32 v127, 0xbfb8aa3b, v125
	v_exp_f32_e32 v126, v126
	v_exp_f32_e32 v127, v127
	v_pk_mul_f32 v[2:3], v[2:3], v[128:129] op_sel_hi:[1,0]
	v_add_f32_e32 v126, 1.0, v126
	v_add_f32_e32 v127, 1.0, v127
	v_rcp_f32_e32 v126, v126
	v_rcp_f32_e32 v127, v127
	s_nop 0
	v_pk_mul_f32 v[124:125], v[124:125], v[126:127]
	s_nop 0
	v_pk_mul_f32 v[122:123], v[122:123], v[124:125]
	v_mul_f32_e32 v124, 0xbfb8aa3b, v116
	v_mul_f32_e32 v125, 0xbfb8aa3b, v117
	v_exp_f32_e32 v124, v124
	v_exp_f32_e32 v125, v125
	v_add_f32_e32 v124, 1.0, v124
	v_add_f32_e32 v125, 1.0, v125
	v_rcp_f32_e32 v124, v124
	v_rcp_f32_e32 v125, v125
	s_nop 0
	v_pk_mul_f32 v[116:117], v[116:117], v[124:125]
	s_nop 0
	v_pk_mul_f32 v[112:113], v[112:113], v[116:117]
	v_pk_mul_f32 v[116:117], v[118:119], v[156:157] op_sel_hi:[1,0]
	s_nop 0
	v_mul_f32_e32 v118, 0xbfb8aa3b, v116
	v_mul_f32_e32 v119, 0xbfb8aa3b, v117
	v_exp_f32_e32 v118, v118
	v_exp_f32_e32 v119, v119
	v_add_f32_e32 v118, 1.0, v118
	v_add_f32_e32 v119, 1.0, v119
	v_rcp_f32_e32 v118, v118
	v_rcp_f32_e32 v119, v119
	s_nop 0
	v_pk_mul_f32 v[116:117], v[116:117], v[118:119]
	s_nop 0
	v_pk_mul_f32 v[118:119], v[114:115], v[116:117]
	v_cvt_pk_bf16_f32 v116, v112, v113
	v_mul_u32_u24_e32 v112, 0xb00, v155
	v_lshlrev_b32_e32 v192, 1, v112
	v_cvt_pk_bf16_f32 v114, v120, v121
	v_cvt_pk_bf16_f32 v115, v122, v123
; __device__ __forceinline__ u32x4 pack8(const f32x4& a, const f32x4& b) { u32x4 w; w.x = pk2(a[0], a[1]); w.y = pk2(a[2], a[3]); w.z = pk2(b[0], b[1]); w.w = pk2(b[2], b[3]); return w; }
; __device__ __forceinline__ float sigm(float x) { return __builtin_amdgcn_rcpf(1.0f + __builtin_amdgcn_exp2f(x * -1.4426950408889634f)); }
;     __device__ __forceinline__ void operator()(const f32x4 (&acc)[2][2][4][2], const Unit& u, int wr, int wc, int fr, int fq) const {
;     ...
;         for (int ai = 0; ai < 2; ++ai)
; #pragma unroll
;             for (int m = 0; m < 4; ++m) { f32x4 o[2];
; #pragma unroll
;                 for (int n = 0; n < 2; ++n) { const f32x4 a = acc[ai][0][m][n] * rx[ai][m], b = acc[ai][1][m][n] * rx[ai][m];
; #pragma unroll
;                     for (int e = 0; e < 4; ++e) o[n][e] = a[e] * sigm(a[e]) * b[e]; }
;                 *(u32x4*)(H + (size_t)(lrow0 + ai * HALF + m * 16) * DFF + col0) = pack8(o[0], o[1]); asm volatile("" ::: "memory"); }
	v_cvt_pk_bf16_f32 v117, v118, v119
	v_lshl_add_u64 v[112:113], v[158:159], 0, v[192:193]
	global_store_dwordx4 v[112:113], v[114:117], off
	s_nop 1
	v_mul_f32_e32 v114, 0xbfb8aa3b, v108
	v_mul_f32_e32 v115, 0xbfb8aa3b, v109
	v_exp_f32_e32 v114, v114
	v_exp_f32_e32 v115, v115
	v_add_f32_e32 v114, 1.0, v114
	v_add_f32_e32 v115, 1.0, v115
	v_rcp_f32_e32 v114, v114
	v_rcp_f32_e32 v115, v115
	s_nop 0
	v_pk_mul_f32 v[108:109], v[108:109], v[114:115]
	s_nop 0
	v_pk_mul_f32 v[104:105], v[104:105], v[108:109]
	v_pk_mul_f32 v[108:109], v[110:111], v[154:155] op_sel_hi:[1,0]
	s_nop 0
	v_mul_f32_e32 v110, 0xbfb8aa3b, v108
	v_mul_f32_e32 v111, 0xbfb8aa3b, v109
	v_exp_f32_e32 v110, v110
	v_exp_f32_e32 v111, v111
	v_add_f32_e32 v110, 1.0, v110
	v_add_f32_e32 v111, 1.0, v111
	v_rcp_f32_e32 v110, v110
	v_rcp_f32_e32 v111, v111
	s_nop 0
	v_pk_mul_f32 v[108:109], v[108:109], v[110:111]
	s_nop 0
	v_pk_mul_f32 v[106:107], v[106:107], v[108:109]
	v_mul_f32_e32 v108, 0xbfb8aa3b, v100
	v_mul_f32_e32 v109, 0xbfb8aa3b, v101
	v_exp_f32_e32 v108, v108
	v_exp_f32_e32 v109, v109
	v_add_f32_e32 v108, 1.0, v108
	v_add_f32_e32 v109, 1.0, v109
	v_rcp_f32_e32 v108, v108
	v_rcp_f32_e32 v109, v109
	s_nop 0
	v_pk_mul_f32 v[100:101], v[100:101], v[108:109]
	s_nop 0
	v_pk_mul_f32 v[100:101], v[96:97], v[100:101]
	v_pk_mul_f32 v[96:97], v[102:103], v[154:155] op_sel_hi:[1,0]
	s_nop 0
	v_mul_f32_e32 v102, 0xbfb8aa3b, v96
	v_mul_f32_e32 v103, 0xbfb8aa3b, v97
	v_exp_f32_e32 v102, v102
	v_exp_f32_e32 v103, v103
	v_add_f32_e32 v102, 1.0, v102
	v_add_f32_e32 v103, 1.0, v103
	v_rcp_f32_e32 v102, v102
	v_rcp_f32_e32 v103, v103
	s_nop 0
	v_pk_mul_f32 v[96:97], v[96:97], v[102:103]
	s_nop 0
	v_pk_mul_f32 v[102:103], v[98:99], v[96:97]
	v_cvt_pk_bf16_f32 v98, v100, v101
	v_add_co_u32_e32 v100, vcc, s69, v112
	v_cvt_pk_bf16_f32 v96, v104, v105
	v_cvt_pk_bf16_f32 v97, v106, v107
	v_cvt_pk_bf16_f32 v99, v102, v103
	v_addc_co_u32_e32 v101, vcc, 0, v113, vcc
	global_store_dwordx4 v[100:101], v[96:99], off
	s_nop 1
	v_mul_f32_e32 v96, 0xbfb8aa3b, v92
	v_mul_f32_e32 v97, 0xbfb8aa3b, v93
	v_exp_f32_e32 v96, v96
	v_exp_f32_e32 v97, v97
	v_add_f32_e32 v96, 1.0, v96
	v_add_f32_e32 v97, 1.0, v97
	v_rcp_f32_e32 v96, v96
	v_rcp_f32_e32 v97, v97
	s_nop 0
	v_pk_mul_f32 v[92:93], v[92:93], v[96:97]
	s_nop 0
	v_pk_mul_f32 v[88:89], v[88:89], v[92:93]
	v_pk_mul_f32 v[92:93], v[94:95], v[152:153] op_sel_hi:[1,0]
	s_nop 0
	v_mul_f32_e32 v94, 0xbfb8aa3b, v92
	v_mul_f32_e32 v95, 0xbfb8aa3b, v93
	v_exp_f32_e32 v94, v94
	v_exp_f32_e32 v95, v95
	v_add_f32_e32 v94, 1.0, v94
	v_add_f32_e32 v95, 1.0, v95
	v_rcp_f32_e32 v94, v94
	v_rcp_f32_e32 v95, v95
	s_nop 0
	v_pk_mul_f32 v[92:93], v[92:93], v[94:95]
	s_nop 0
	v_pk_mul_f32 v[90:91], v[90:91], v[92:93]
	v_mul_f32_e32 v92, 0xbfb8aa3b, v84
	v_mul_f32_e32 v93, 0xbfb8aa3b, v85
	v_exp_f32_e32 v92, v92
	v_exp_f32_e32 v93, v93
	v_add_f32_e32 v92, 1.0, v92
	v_add_f32_e32 v93, 1.0, v93
	v_rcp_f32_e32 v92, v92
	v_rcp_f32_e32 v93, v93
	s_nop 0
	v_pk_mul_f32 v[84:85], v[84:85], v[92:93]
	s_nop 0
	v_pk_mul_f32 v[84:85], v[80:81], v[84:85]
	v_pk_mul_f32 v[80:81], v[86:87], v[152:153] op_sel_hi:[1,0]
	s_nop 0
	v_mul_f32_e32 v86, 0xbfb8aa3b, v80
	v_mul_f32_e32 v87, 0xbfb8aa3b, v81
	v_exp_f32_e32 v86, v86
	v_exp_f32_e32 v87, v87
	v_add_f32_e32 v86, 1.0, v86
	v_add_f32_e32 v87, 1.0, v87
	v_rcp_f32_e32 v86, v86
	v_rcp_f32_e32 v87, v87
	s_nop 0
	v_pk_mul_f32 v[80:81], v[80:81], v[86:87]
	s_nop 0
	v_pk_mul_f32 v[86:87], v[82:83], v[80:81]
	v_cvt_pk_bf16_f32 v82, v84, v85
	v_add_co_u32_e32 v84, vcc, s73, v112
	v_cvt_pk_bf16_f32 v80, v88, v89
	v_cvt_pk_bf16_f32 v81, v90, v91
	v_cvt_pk_bf16_f32 v83, v86, v87
	v_addc_co_u32_e32 v85, vcc, 0, v113, vcc
	global_store_dwordx4 v[84:85], v[80:83], off
	s_nop 1
	v_mul_f32_e32 v80, 0xbfb8aa3b, v76
	v_mul_f32_e32 v81, 0xbfb8aa3b, v77
	v_exp_f32_e32 v80, v80
	v_exp_f32_e32 v81, v81
	v_add_f32_e32 v80, 1.0, v80
	v_add_f32_e32 v81, 1.0, v81
	v_rcp_f32_e32 v80, v80
	v_rcp_f32_e32 v81, v81
	s_nop 0
	v_pk_mul_f32 v[76:77], v[76:77], v[80:81]
	s_nop 0
	v_pk_mul_f32 v[72:73], v[72:73], v[76:77]
	v_pk_mul_f32 v[76:77], v[78:79], v[150:151] op_sel_hi:[1,0]
	s_nop 0
	v_mul_f32_e32 v78, 0xbfb8aa3b, v76
	v_mul_f32_e32 v79, 0xbfb8aa3b, v77
	v_exp_f32_e32 v78, v78
	v_exp_f32_e32 v79, v79
	v_add_f32_e32 v78, 1.0, v78
	v_add_f32_e32 v79, 1.0, v79
	v_rcp_f32_e32 v78, v78
	v_rcp_f32_e32 v79, v79
	s_nop 0
	v_pk_mul_f32 v[76:77], v[76:77], v[78:79]
	s_nop 0
	v_pk_mul_f32 v[74:75], v[74:75], v[76:77]
	v_mul_f32_e32 v76, 0xbfb8aa3b, v68
	v_mul_f32_e32 v77, 0xbfb8aa3b, v69
	v_exp_f32_e32 v76, v76
	v_exp_f32_e32 v77, v77
	v_add_f32_e32 v76, 1.0, v76
	v_add_f32_e32 v77, 1.0, v77
	v_rcp_f32_e32 v76, v76
	v_rcp_f32_e32 v77, v77
	s_nop 0
	v_pk_mul_f32 v[68:69], v[68:69], v[76:77]
	s_nop 0
	v_pk_mul_f32 v[68:69], v[64:65], v[68:69]
	v_pk_mul_f32 v[64:65], v[70:71], v[150:151] op_sel_hi:[1,0]
	s_nop 0
	v_mul_f32_e32 v70, 0xbfb8aa3b, v64
	v_mul_f32_e32 v71, 0xbfb8aa3b, v65
	v_exp_f32_e32 v70, v70
	v_exp_f32_e32 v71, v71
	v_add_f32_e32 v70, 1.0, v70
	v_add_f32_e32 v71, 1.0, v71
	v_rcp_f32_e32 v70, v70
	v_rcp_f32_e32 v71, v71
	s_nop 0
	v_pk_mul_f32 v[64:65], v[64:65], v[70:71]
	s_nop 0
	v_pk_mul_f32 v[70:71], v[66:67], v[64:65]
	v_cvt_pk_bf16_f32 v66, v68, v69
	v_add_co_u32_e32 v68, vcc, s74, v112
	v_cvt_pk_bf16_f32 v64, v72, v73
	v_cvt_pk_bf16_f32 v65, v74, v75
	v_cvt_pk_bf16_f32 v67, v70, v71
	v_addc_co_u32_e32 v69, vcc, 0, v113, vcc
	global_store_dwordx4 v[68:69], v[64:67], off
	s_nop 1
	v_mul_f32_e32 v64, 0xbfb8aa3b, v60
	v_mul_f32_e32 v65, 0xbfb8aa3b, v61
	v_exp_f32_e32 v64, v64
	v_exp_f32_e32 v65, v65
	v_add_f32_e32 v64, 1.0, v64
	v_add_f32_e32 v65, 1.0, v65
	v_rcp_f32_e32 v64, v64
; __device__ __forceinline__ u32x4 pack8(const f32x4& a, const f32x4& b) { u32x4 w; w.x = pk2(a[0], a[1]); w.y = pk2(a[2], a[3]); w.z = pk2(b[0], b[1]); w.w = pk2(b[2], b[3]); return w; }
; __device__ __forceinline__ float sigm(float x) { return __builtin_amdgcn_rcpf(1.0f + __builtin_amdgcn_exp2f(x * -1.4426950408889634f)); }
;     __device__ __forceinline__ void operator()(const f32x4 (&acc)[2][2][4][2], const Unit& u, int wr, int wc, int fr, int fq) const {
;     ...
;         for (int ai = 0; ai < 2; ++ai)
; #pragma unroll
;             for (int m = 0; m < 4; ++m) { f32x4 o[2];
; #pragma unroll
;                 for (int n = 0; n < 2; ++n) { const f32x4 a = acc[ai][0][m][n] * rx[ai][m], b = acc[ai][1][m][n] * rx[ai][m];
; #pragma unroll
;                     for (int e = 0; e < 4; ++e) o[n][e] = a[e] * sigm(a[e]) * b[e]; }
;                 *(u32x4*)(H + (size_t)(lrow0 + ai * HALF + m * 16) * DFF + col0) = pack8(o[0], o[1]); asm volatile("" ::: "memory"); }
	v_rcp_f32_e32 v65, v65
	s_nop 0
	v_pk_mul_f32 v[60:61], v[60:61], v[64:65]
	s_nop 0
	v_pk_mul_f32 v[56:57], v[56:57], v[60:61]
	v_pk_mul_f32 v[60:61], v[62:63], v[148:149] op_sel_hi:[1,0]
	s_nop 0
	v_mul_f32_e32 v62, 0xbfb8aa3b, v60
	v_mul_f32_e32 v63, 0xbfb8aa3b, v61
	v_exp_f32_e32 v62, v62
	v_exp_f32_e32 v63, v63
	v_add_f32_e32 v62, 1.0, v62
	v_add_f32_e32 v63, 1.0, v63
	v_rcp_f32_e32 v62, v62
	v_rcp_f32_e32 v63, v63
	s_nop 0
	v_pk_mul_f32 v[60:61], v[60:61], v[62:63]
	s_nop 0
	v_pk_mul_f32 v[58:59], v[58:59], v[60:61]
	v_mul_f32_e32 v60, 0xbfb8aa3b, v52
	v_mul_f32_e32 v61, 0xbfb8aa3b, v53
	v_exp_f32_e32 v60, v60
	v_exp_f32_e32 v61, v61
	v_add_f32_e32 v60, 1.0, v60
	v_add_f32_e32 v61, 1.0, v61
	v_rcp_f32_e32 v60, v60
	v_rcp_f32_e32 v61, v61
	s_nop 0
	v_pk_mul_f32 v[52:53], v[52:53], v[60:61]
	s_nop 0
	v_pk_mul_f32 v[52:53], v[48:49], v[52:53]
	v_pk_mul_f32 v[48:49], v[54:55], v[148:149] op_sel_hi:[1,0]
	s_nop 0
	v_mul_f32_e32 v54, 0xbfb8aa3b, v48
	v_mul_f32_e32 v55, 0xbfb8aa3b, v49
	v_exp_f32_e32 v54, v54
	v_exp_f32_e32 v55, v55
	v_add_f32_e32 v54, 1.0, v54
	v_add_f32_e32 v55, 1.0, v55
	v_rcp_f32_e32 v54, v54
	v_rcp_f32_e32 v55, v55
	s_nop 0
	v_pk_mul_f32 v[48:49], v[48:49], v[54:55]
	s_nop 0
	v_pk_mul_f32 v[54:55], v[50:51], v[48:49]
	v_cvt_pk_bf16_f32 v50, v52, v53
	v_add_co_u32_e32 v52, vcc, s75, v112
	v_cvt_pk_bf16_f32 v48, v56, v57
	v_cvt_pk_bf16_f32 v49, v58, v59
	v_cvt_pk_bf16_f32 v51, v54, v55
	v_addc_co_u32_e32 v53, vcc, 0, v113, vcc
	global_store_dwordx4 v[52:53], v[48:51], off
	s_nop 1
	v_mul_f32_e32 v48, 0xbfb8aa3b, v44
	v_mul_f32_e32 v49, 0xbfb8aa3b, v45
	v_exp_f32_e32 v48, v48
	v_exp_f32_e32 v49, v49
	v_add_f32_e32 v48, 1.0, v48
	v_add_f32_e32 v49, 1.0, v49
	v_rcp_f32_e32 v48, v48
	v_rcp_f32_e32 v49, v49
	s_nop 0
	v_pk_mul_f32 v[44:45], v[44:45], v[48:49]
	s_nop 0
	v_pk_mul_f32 v[40:41], v[40:41], v[44:45]
	v_pk_mul_f32 v[44:45], v[46:47], v[146:147] op_sel_hi:[1,0]
	s_nop 0
	v_mul_f32_e32 v46, 0xbfb8aa3b, v44
	v_mul_f32_e32 v47, 0xbfb8aa3b, v45
	v_exp_f32_e32 v46, v46
	v_exp_f32_e32 v47, v47
	v_add_f32_e32 v46, 1.0, v46
	v_add_f32_e32 v47, 1.0, v47
	v_rcp_f32_e32 v46, v46
	v_rcp_f32_e32 v47, v47
	s_nop 0
	v_pk_mul_f32 v[44:45], v[44:45], v[46:47]
	s_nop 0
	v_pk_mul_f32 v[42:43], v[42:43], v[44:45]
	v_mul_f32_e32 v44, 0xbfb8aa3b, v36
	v_mul_f32_e32 v45, 0xbfb8aa3b, v37
	v_exp_f32_e32 v44, v44
	v_exp_f32_e32 v45, v45
	v_add_f32_e32 v44, 1.0, v44
	v_add_f32_e32 v45, 1.0, v45
	v_rcp_f32_e32 v44, v44
	v_rcp_f32_e32 v45, v45
	s_nop 0
	v_pk_mul_f32 v[36:37], v[36:37], v[44:45]
	s_nop 0
	v_pk_mul_f32 v[36:37], v[32:33], v[36:37]
	v_pk_mul_f32 v[32:33], v[38:39], v[146:147] op_sel_hi:[1,0]
	s_nop 0
	v_mul_f32_e32 v38, 0xbfb8aa3b, v32
	v_mul_f32_e32 v39, 0xbfb8aa3b, v33
	v_exp_f32_e32 v38, v38
	v_exp_f32_e32 v39, v39
	v_add_f32_e32 v38, 1.0, v38
	v_add_f32_e32 v39, 1.0, v39
	v_rcp_f32_e32 v38, v38
	v_rcp_f32_e32 v39, v39
	s_nop 0
	v_pk_mul_f32 v[32:33], v[32:33], v[38:39]
	s_nop 0
	v_pk_mul_f32 v[38:39], v[34:35], v[32:33]
	v_cvt_pk_bf16_f32 v34, v36, v37
	v_add_co_u32_e32 v36, vcc, s76, v112
	v_cvt_pk_bf16_f32 v32, v40, v41
	v_cvt_pk_bf16_f32 v33, v42, v43
	v_cvt_pk_bf16_f32 v35, v38, v39
	v_addc_co_u32_e32 v37, vcc, 0, v113, vcc
	global_store_dwordx4 v[36:37], v[32:35], off
	s_nop 1
	v_mul_f32_e32 v32, 0xbfb8aa3b, v28
	v_mul_f32_e32 v33, 0xbfb8aa3b, v29
	v_exp_f32_e32 v32, v32
	v_exp_f32_e32 v33, v33
	v_add_f32_e32 v32, 1.0, v32
	v_add_f32_e32 v33, 1.0, v33
	v_rcp_f32_e32 v32, v32
	v_rcp_f32_e32 v33, v33
	s_nop 0
	v_pk_mul_f32 v[28:29], v[28:29], v[32:33]
	s_nop 0
	v_pk_mul_f32 v[24:25], v[24:25], v[28:29]
	v_pk_mul_f32 v[28:29], v[30:31], v[130:131] op_sel_hi:[1,0]
	s_nop 0
	v_mul_f32_e32 v30, 0xbfb8aa3b, v28
	v_mul_f32_e32 v31, 0xbfb8aa3b, v29
	v_exp_f32_e32 v30, v30
	v_exp_f32_e32 v31, v31
	v_add_f32_e32 v30, 1.0, v30
	v_add_f32_e32 v31, 1.0, v31
	v_rcp_f32_e32 v30, v30
	v_rcp_f32_e32 v31, v31
	s_nop 0
	v_pk_mul_f32 v[28:29], v[28:29], v[30:31]
	s_nop 0
	v_pk_mul_f32 v[26:27], v[26:27], v[28:29]
	v_mul_f32_e32 v28, 0xbfb8aa3b, v20
	v_mul_f32_e32 v29, 0xbfb8aa3b, v21
	v_exp_f32_e32 v28, v28
	v_exp_f32_e32 v29, v29
	v_add_f32_e32 v28, 1.0, v28
	v_add_f32_e32 v29, 1.0, v29
	v_rcp_f32_e32 v28, v28
	v_rcp_f32_e32 v29, v29
	s_nop 0
	v_pk_mul_f32 v[20:21], v[20:21], v[28:29]
	s_nop 0
	v_pk_mul_f32 v[20:21], v[16:17], v[20:21]
	v_pk_mul_f32 v[16:17], v[22:23], v[130:131] op_sel_hi:[1,0]
	s_nop 0
	v_mul_f32_e32 v22, 0xbfb8aa3b, v16
	v_mul_f32_e32 v23, 0xbfb8aa3b, v17
	v_exp_f32_e32 v22, v22
	v_exp_f32_e32 v23, v23
	v_add_f32_e32 v22, 1.0, v22
	v_add_f32_e32 v23, 1.0, v23
	v_rcp_f32_e32 v22, v22
	v_rcp_f32_e32 v23, v23
	s_nop 0
	v_pk_mul_f32 v[16:17], v[16:17], v[22:23]
	s_nop 0
	v_pk_mul_f32 v[22:23], v[18:19], v[16:17]
	v_cvt_pk_bf16_f32 v18, v20, v21
	v_add_co_u32_e32 v20, vcc, s77, v112
	v_cvt_pk_bf16_f32 v16, v24, v25
	v_cvt_pk_bf16_f32 v17, v26, v27
	v_cvt_pk_bf16_f32 v19, v22, v23
	v_addc_co_u32_e32 v21, vcc, 0, v113, vcc
	global_store_dwordx4 v[20:21], v[16:19], off
	s_nop 1
	v_mul_f32_e32 v16, 0xbfb8aa3b, v12
	v_mul_f32_e32 v17, 0xbfb8aa3b, v13
	v_exp_f32_e32 v16, v16
	v_exp_f32_e32 v17, v17
	v_add_f32_e32 v16, 1.0, v16
	v_add_f32_e32 v17, 1.0, v17
	v_rcp_f32_e32 v16, v16
	v_rcp_f32_e32 v17, v17
	s_nop 0
	v_pk_mul_f32 v[12:13], v[12:13], v[16:17]
	s_nop 0
	v_pk_mul_f32 v[8:9], v[8:9], v[12:13]
	v_pk_mul_f32 v[12:13], v[14:15], v[128:129] op_sel_hi:[1,0]
	s_nop 0
	v_mul_f32_e32 v14, 0xbfb8aa3b, v12
	v_mul_f32_e32 v15, 0xbfb8aa3b, v13
	v_exp_f32_e32 v14, v14
	v_exp_f32_e32 v15, v15
	v_add_f32_e32 v14, 1.0, v14
	v_add_f32_e32 v15, 1.0, v15
	v_rcp_f32_e32 v14, v14
	v_rcp_f32_e32 v15, v15
	s_nop 0
	v_pk_mul_f32 v[12:13], v[12:13], v[14:15]
	s_nop 0
	v_pk_mul_f32 v[10:11], v[10:11], v[12:13]
	v_mul_f32_e32 v12, 0xbfb8aa3b, v4
	v_mul_f32_e32 v13, 0xbfb8aa3b, v5
	v_exp_f32_e32 v12, v12
	v_exp_f32_e32 v13, v13
	v_add_f32_e32 v12, 1.0, v12
	v_add_f32_e32 v13, 1.0, v13
	v_rcp_f32_e32 v12, v12
	v_rcp_f32_e32 v13, v13
	s_nop 0
	v_pk_mul_f32 v[4:5], v[4:5], v[12:13]
	s_nop 0
	v_pk_mul_f32 v[4:5], v[0:1], v[4:5]
	v_pk_mul_f32 v[0:1], v[6:7], v[128:129] op_sel_hi:[1,0]
	s_nop 0
	v_mul_f32_e32 v6, 0xbfb8aa3b, v0
	v_mul_f32_e32 v7, 0xbfb8aa3b, v1
	v_exp_f32_e32 v6, v6
	v_exp_f32_e32 v7, v7
	v_add_f32_e32 v6, 1.0, v6
	v_add_f32_e32 v7, 1.0, v7
	v_rcp_f32_e32 v6, v6
	v_rcp_f32_e32 v7, v7
	s_nop 0
	v_pk_mul_f32 v[0:1], v[0:1], v[6:7]
	s_nop 0
	v_pk_mul_f32 v[6:7], v[2:3], v[0:1]
	v_cvt_pk_bf16_f32 v2, v4, v5
	v_add_co_u32_e32 v4, vcc, 0xf2000, v112
	v_cvt_pk_bf16_f32 v0, v8, v9
	v_cvt_pk_bf16_f32 v1, v10, v11
	v_cvt_pk_bf16_f32 v3, v6, v7
	v_addc_co_u32_e32 v5, vcc, 0, v113, vcc
	global_store_dwordx4 v[4:5], v[0:3], off
	s_andn2_b64 vcc, exec, s[40:41]
	s_cbranch_vccnz .LBB0_573
	s_andn2_b64 vcc, exec, s[22:23]
	s_cbranch_vccnz .LBB0_572
	s_barrier
	s_branch .LBB0_572
